# speedup vs baseline: 1.0071x; 1.0071x over previous
; DEVI u16 f2bf(float x) { return (u16)(cvtpk(x, 0.f) & 0xffffu); }
; DEVI void phase_prep(const Params& p, char* shm, const int wid_s_) {
;     ...
;   constexpr int J0 = 244 * 8, J1 = J0 + 48 * 2, J2 = J1 + 64 * 2, J5 = J2 + 3 * 256;
;   for (int job = blockIdx.x; job < J5; job += gridDim.x) {
;     int which, jb, kb, Nsrc, K; const float* W; const float* sc; u16* Bt;
;     if (job < J0)      { which = 0; jb = job >> 3; kb = job & 7; Nsrc = 15424; K = 2048; W = p.w_in; sc = p.norm_w; Bt = (u16*)(p.ws + O_WIN); }
;     else if (job < J1) { int q = job - J0; which = 1; jb = q >> 1; kb = q & 1; Nsrc = 3072; K = 512; W = p.w_uq; sc = p.qn_w; Bt = (u16*)(p.ws + O_WUQ); }
;     else if (job < J2) { int q = job - J1; which = 2; jb = q >> 1; kb = q & 1; Nsrc = 4096; K = 512; W = p.w_ukv; sc = p.kvn_w; Bt = (u16*)(p.ws + O_WUKV); }
;     else { int q = job - J2, mth = q >> 8; q &= 255; which = 2; jb = q >> 3; kb = q & 7; Nsrc = 2048; K = 2048; sc = nullptr;
;            W = mth == 0 ? p.w_oa : (mth == 1 ? p.w_oc : p.w_o); Bt = (u16*)(p.ws + (mth == 0 ? O_WOA : (mth == 1 ? O_WOC : O_WO))); }
;     const int j0 = jb * 64, k0 = kb * 256, jl = t & 63, kq = t >> 6;
;     const int s = src_of(which, j0 + jl);
;     float v[32];
; #pragma unroll
;     for (int i = 0; i < 32; ++i) { const int k = k0 + kq + 8 * i; v[i] = (s >= 0) ? __builtin_nontemporal_load(W + (size_t)k * Nsrc + s) : 0.f; }
;     if (sc) {
; #pragma unroll
;       for (int i = 0; i < 32; ++i) v[i] *= sc[k0 + kq + 8 * i];
;     }
; #pragma unroll
;     for (int i = 0; i < 32; ++i) tile[jl * 264 + kq + 8 * i] = f2bf(v[i]);
;     __syncthreads();
; #pragma unroll
;     for (int q = 0; q < 4; ++q) { const int c = t + 512 * q, r = c >> 5, c16 = c & 31;
;       *(uint4*)(Bt + (size_t)(j0 + r) * K + k0 + c16 * 8) = *(const uint4*)(tile + r * 264 + c16 * 8); }
; __global__ void __launch_bounds__(512) fwd_megakernel(Params p) {
;   __shared__ __attribute__((aligned(1024))) char shm[131072];
;   cg::grid_group grid = cg::this_grid();
;   const int wid_s_ = __builtin_amdgcn_readfirstlane((int)(threadIdx.x >> 6));
;   phase_prep(p, shm, wid_s_);
_Z14fwd_megakernel6Params:
	s_mov_b64 s[56:57], s[0:1]
	s_mov_b32 s99, 0
	s_load_dword s85, s[0:1], 0x88
	v_and_b32_e32 v1, 0x3ff, v0
	s_add_u32 s58, s56, 0x88
	v_readfirstlane_b32 s0, v1
	v_mbcnt_lo_u32_b32 v2, -1, 0
	s_addc_u32 s59, s57, 0
	s_andn2_b32 s0, s0, 63
	v_mbcnt_hi_u32_b32 v2, -1, v2
	v_or_b32_e32 v207, s0, v2
	v_mov_b32_e32 v50, v207
	v_writelane_b32 v254, s2, 0
	s_cmpk_gt_i32 s2, 0xb7f
	s_cbranch_scc1 .LBB0_107
	v_mov_b32_e32 v2, 0x900
	v_and_or_b32 v56, v50, 15, v2
	v_lshlrev_b32_e32 v2, 1, v50
	v_ashrrev_i32_e32 v52, 6, v50
	v_bfe_u32 v53, v50, 5, 1
	v_and_b32_e32 v2, 62, v2
	s_movk_i32 s0, 0x400
	v_and_b32_e32 v51, 63, v50
	v_or3_b32 v57, v53, v2, s0
	v_lshlrev_b32_e32 v2, 1, v52
	s_movk_i32 s2, 0x210
	v_mad_u32_u24 v58, v51, s2, v2
	v_lshlrev_b32_e32 v2, 3, v50
	v_and_b32_e32 v2, 0xf8, v2
	v_lshlrev_b32_e32 v10, 1, v2
	v_ashrrev_i32_e32 v59, 5, v50
	v_mad_u64_u32 v[4:5], s[0:1], v59, s2, v[10:11]
	s_add_u32 s4, s56, 0x48
	v_add_u32_e32 v5, 0x200, v50
	s_addc_u32 s5, s57, 0
	v_ashrrev_i32_e32 v5, 5, v5
	s_load_dwordx2 s[10:11], s[56:57], 0x80
	s_add_u32 s6, s56, 56
	v_mad_u64_u32 v[6:7], s[0:1], v5, s2, v[10:11]
	s_addc_u32 s7, s57, 0
	v_add_u32_e32 v7, 0x400, v50
	s_add_u32 s8, s56, 32
	v_ashrrev_i32_e32 v7, 5, v7
	s_load_dwordx2 s[12:13], s[56:57], 0x18
	s_load_dwordx2 s[14:15], s[56:57], 0x30
	s_load_dwordx2 s[16:17], s[56:57], 0x40
	s_addc_u32 s9, s57, 0
	v_mad_u64_u32 v[8:9], s[0:1], v7, s2, v[10:11]
	v_add_u32_e32 v9, 0x600, v50
	s_waitcnt lgkmcnt(0)
	s_add_u32 s18, s10, 0x4000000
	v_ashrrev_i32_e32 v9, 5, v9
	s_addc_u32 s19, s11, 0
	v_bfe_u32 v54, v50, 4, 2
	v_mad_u64_u32 v[10:11], s[0:1], v9, s2, v[10:11]
	s_add_u32 s20, s10, 0x3d00000
	v_or_b32_e32 v55, 0xffffff40, v54
	v_mov_b32_e32 v3, 0
	s_addc_u32 s21, s11, 0
	s_movk_i32 s0, 0x60
	s_mov_b32 s1, 0x4c00000
	v_mov_b32_e32 v11, 0xff
	s_movk_i32 s2, 0xc0
	v_lshlrev_b32_e32 v12, 1, v2
	v_readlane_b32 s3, v254, 0
	s_branch .LBB0_3

; __global__ void __launch_bounds__(512) fwd_megakernel(Params p) {
;     ...
;     grid.sync();
.LBB0_155:
	s_or_b64 exec, exec, s[4:5]
	s_waitcnt lgkmcnt(0)
	s_waitcnt vmcnt(0)
	s_barrier
	s_mov_b64 s[4:5], exec
	v_readlane_b32 s6, v254, 5
	v_readlane_b32 s7, v254, 6
	s_and_b64 s[6:7], s[4:5], s[6:7]
	s_mov_b64 exec, s[6:7]
	s_cbranch_execz .LBB0_165
	s_cmp_lg_u32 s99, 0
	s_cbranch_scc1 .Lgbar_init_skip
	v_readlane_b32 s100, v254, 56
	v_readlane_b32 s101, v254, 57
	s_nop 4
	s_load_dwordx2 s[100:101], s[100:101], 0x78
	s_waitcnt lgkmcnt(0)
	s_add_u32 s100, s100, 0x1fffffc0
	s_addc_u32 s101, s101, 0
	global_store_dword v205, v205, s[100:101] sc0 sc1
.Lgbar_init_skip:
	buffer_wbl2 sc1
	s_waitcnt vmcnt(0)
	s_load_dwordx2 s[6:7], s[58:59], 0x58
	s_mov_b64 s[8:9], exec
	v_mbcnt_lo_u32_b32 v1, s8, 0
	v_mbcnt_hi_u32_b32 v1, s9, v1
	v_cmp_eq_u32_e32 vcc, 0, v1
	s_waitcnt lgkmcnt(0)
	global_load_dword v0, v205, s[6:7] offset:40
	s_and_saveexec_b64 s[12:13], vcc
	s_cbranch_execz .LBB0_158
	s_bcnt1_i32_b64 s1, s[8:9]
	v_mov_b32_e32 v2, s1
	global_atomic_add v2, v205, v2, s[6:7] offset:32 sc0
.LBB0_158:
	s_or_b64 exec, exec, s[12:13]
	s_waitcnt vmcnt(0)
	v_readfirstlane_b32 s98, v0
	v_readfirstlane_b32 s1, v2
	v_add_u32_e32 v2, -1, v0
	s_nop 0
	v_add_u32_e32 v1, s1, v1
	v_cmp_eq_u32_sdwa s[12:13], v1, v2 src0_sel:WORD_0 src1_sel:DWORD
	s_and_saveexec_b64 s[8:9], s[12:13]
	s_cbranch_execz .LBB0_161
	s_mov_b64 s[12:13], exec
	v_mbcnt_lo_u32_b32 v2, s12, 0
	v_mbcnt_hi_u32_b32 v2, s13, v2
	v_cmp_eq_u32_e32 vcc, 0, v2
	s_and_b64 s[16:17], exec, vcc
	s_mov_b64 exec, s[16:17]
	s_cbranch_execz .LBB0_161
	v_sub_u32_e32 v0, 0x10000, v0
	s_bcnt1_i32_b64 s1, s[12:13]
	v_mul_lo_u32 v0, v0, s1
	global_atomic_add v205, v0, s[6:7] offset:32

; __global__ void __launch_bounds__(512) fwd_megakernel(Params p) {
;     ...
;     grid.sync();
.LBB0_609:
	s_waitcnt vmcnt(0)
	s_barrier
	s_mov_b64 s[4:5], exec
	v_readlane_b32 s6, v254, 5
	v_readlane_b32 s7, v254, 6
	s_and_b64 s[6:7], s[4:5], s[6:7]
	v_readlane_b32 s20, v254, 60
	v_readlane_b32 s21, v254, 61
	s_movk_i32 s24, 0xc0
	s_mul_i32 s25, s61, 0xc0
	v_readlane_b32 s31, v255, 1
	v_readlane_b32 s35, v255, 2
	v_readlane_b32 s26, v255, 3
	v_readlane_b32 s27, v255, 4
	v_readlane_b32 s55, v254, 45
	s_mov_b64 exec, s[6:7]
	s_cbranch_execz .LBB0_619
	buffer_wbl2 sc1
	s_waitcnt vmcnt(0)
	v_readlane_b32 s100, v254, 56
	v_readlane_b32 s101, v254, 57
	s_nop 4
	s_load_dwordx2 s[100:101], s[100:101], 0x78
	s_add_u32 s99, s99, 1
	s_mul_i32 s1, s98, s99
	v_mov_b32_e32 v1, 1
	s_waitcnt lgkmcnt(0)
	s_add_u32 s100, s100, 0x1fffffc0
	s_addc_u32 s101, s101, 0
	global_atomic_add v205, v1, s[100:101]
.Lgbar_poll_1:
	global_load_dword v0, v205, s[100:101] sc1
	s_waitcnt vmcnt(0)
	v_readfirstlane_b32 s8, v0
	s_nop 0
	s_cmp_ge_u32 s8, s1
	s_cbranch_scc1 .Lgbar_done_1
	s_sleep 2
	s_branch .Lgbar_poll_1

; __global__ void __launch_bounds__(512) fwd_megakernel(Params p) {
;     ...
;     grid.sync();
.LBB0_639:
	s_waitcnt lgkmcnt(0)
	s_waitcnt vmcnt(0)
	s_barrier
	s_mov_b64 s[4:5], exec
	v_readlane_b32 s6, v254, 5
	v_readlane_b32 s7, v254, 6
	s_and_b64 s[6:7], s[4:5], s[6:7]
	s_mov_b64 exec, s[6:7]
	s_cbranch_execz .LBB0_649
	buffer_wbl2 sc1
	s_waitcnt vmcnt(0)
	v_readlane_b32 s100, v254, 56
	v_readlane_b32 s101, v254, 57
	s_nop 4
	s_load_dwordx2 s[100:101], s[100:101], 0x78
	s_add_u32 s99, s99, 1
	s_mul_i32 s1, s98, s99
	v_mov_b32_e32 v1, 1
	s_waitcnt lgkmcnt(0)
	s_add_u32 s100, s100, 0x1fffffc0
	s_addc_u32 s101, s101, 0
	global_atomic_add v205, v1, s[100:101]

; __global__ void __launch_bounds__(512) fwd_megakernel(Params p) {
;     ...
;     grid.sync();
.LBB0_655:
	s_waitcnt vmcnt(0)
	s_barrier
	s_mov_b64 s[6:7], exec
	v_readlane_b32 s4, v254, 5
	v_readlane_b32 s5, v254, 6
	s_and_b64 s[4:5], s[6:7], s[4:5]
	s_mov_b64 exec, s[4:5]
	s_cbranch_execz .LBB0_665
	buffer_wbl2 sc1
	s_waitcnt vmcnt(0)
	v_readlane_b32 s100, v254, 56
	v_readlane_b32 s101, v254, 57
	s_nop 4
	s_load_dwordx2 s[100:101], s[100:101], 0x78
	s_add_u32 s99, s99, 1
	s_mul_i32 s1, s98, s99
	v_mov_b32_e32 v1, 1
	s_waitcnt lgkmcnt(0)
	s_add_u32 s100, s100, 0x1fffffc0
	s_addc_u32 s101, s101, 0
	global_atomic_add v205, v1, s[100:101]

; __global__ void __launch_bounds__(512) fwd_megakernel(Params p) {
;     ...
;     grid.sync();
.LBB0_967:
	s_or_b64 exec, exec, s[6:7]
	s_waitcnt vmcnt(0)
	s_barrier
	s_mov_b64 s[6:7], exec
	v_readlane_b32 s4, v254, 5
	v_readlane_b32 s5, v254, 6
	s_and_b64 s[4:5], s[6:7], s[4:5]
	s_mov_b64 exec, s[4:5]
	s_cbranch_execz .LBB0_977
	buffer_wbl2 sc1
	s_waitcnt vmcnt(0)
	v_readlane_b32 s100, v254, 56
	v_readlane_b32 s101, v254, 57
	s_nop 4
	s_load_dwordx2 s[100:101], s[100:101], 0x78
	s_add_u32 s99, s99, 1
	s_mul_i32 s1, s98, s99
	v_mov_b32_e32 v1, 1
	s_waitcnt lgkmcnt(0)
	s_add_u32 s100, s100, 0x1fffffc0
	s_addc_u32 s101, s101, 0
	global_atomic_add v205, v1, s[100:101]

; DEVI void phase_e(const Params& p, const Pass& ps, char* shm, const int wid_s_) {
;     ...
;   const int nqb = ps.S >> 8, items = ps.nb * 16 * nqb, per = gridDim.x >> 3, xcd = blockIdx.x & 7, slot = blockIdx.x >> 3;
;   const int NT = ps.Lpad >> 6;
;   for (int it = 0;; ++it) {
;     int item = (it * 8 + xcd) * per + slot; if (item >= items) break;
;     int qb = item % nqb, bh = item / nqb, h = bh & 15, b = bh >> 4;
;     size_t row0 = (size_t)b * ps.S + (size_t)qb * 256;
;     attn_item(Q + row0 * LDQ + h * 192, KN + (size_t)b * ps.Lpad * LDK + h * 128, VT + (size_t)((b * 16 + h) * 128) * ps.Lpad, ps.Lpad, KR + (size_t)b * ps.Lpad * 64,
.LBB0_977:
	s_or_b64 exec, exec, s[6:7]
	s_lshr_b32 s1, s29, 8
	s_mul_i32 s2, s22, s1
	s_lshl_b32 s55, s2, 4
	s_cmp_ge_u32 s34, s55
	s_barrier
	s_cbranch_scc1 .LBB0_998
	s_lshr_b32 s4, s28, 6
	s_lshl_b32 s5, s28, 1
	s_add_i32 s31, s1, -1
	s_ff1_i32_b32 s93, s1
	s_lshl_b32 s64, s28, 1
	s_mov_b32 s12, 0
	s_mov_b32 s1, s34
	s_mov_b32 s34, 0
	v_readfirstlane_b32 s100, v207
	s_lshr_b32 s100, s100, 6
	s_cmp_ge_u32 s100, 4
	s_cbranch_scc0 .Lprio_skip
	s_setprio 1

; __global__ void __launch_bounds__(512) fwd_megakernel(Params p) {
;     ...
;     grid.sync();
.LBB0_998:
	s_setprio 0
	s_waitcnt vmcnt(0)
	s_barrier
	s_mov_b64 s[6:7], exec
	v_readlane_b32 s4, v254, 5
	v_readlane_b32 s5, v254, 6
	s_and_b64 s[4:5], s[6:7], s[4:5]
	v_readlane_b32 s18, v254, 63
	v_readlane_b32 s19, v255, 0
	v_readlane_b32 s20, v255, 5
	v_readlane_b32 s21, v255, 6
	v_readlane_b32 s22, v255, 7
	v_readlane_b32 s26, v254, 60
	v_readlane_b32 s27, v254, 61
	v_readlane_b32 s31, v255, 1
	v_readlane_b32 s35, v255, 2
	v_readlane_b32 s54, v255, 3
	v_readlane_b32 s55, v255, 4
	s_mov_b64 exec, s[4:5]
	s_cbranch_execz .LBB0_1008
	buffer_wbl2 sc1
	s_waitcnt vmcnt(0)
	v_readlane_b32 s100, v254, 56
	v_readlane_b32 s101, v254, 57
	s_nop 4
	s_load_dwordx2 s[100:101], s[100:101], 0x78
	s_add_u32 s99, s99, 1
	s_mul_i32 s1, s98, s99
	v_mov_b32_e32 v1, 1
	s_waitcnt lgkmcnt(0)
	s_add_u32 s100, s100, 0x1fffffc0
	s_addc_u32 s101, s101, 0
	global_atomic_add v205, v1, s[100:101]

; __global__ void __launch_bounds__(512) fwd_megakernel(Params p) {
;     ...
;     grid.sync();
.LBB0_1030:
	s_waitcnt vmcnt(0)
	s_barrier
	s_mov_b64 s[4:5], exec
	v_readlane_b32 s6, v254, 5
	v_readlane_b32 s7, v254, 6
	s_and_b64 s[6:7], s[4:5], s[6:7]
	s_mov_b64 s[16:17], 0x1000
	s_mov_b64 s[24:25], 0x1400
	s_mov_b64 s[28:29], 0x1800
	s_mov_b64 s[96:97], 0x1c00
	s_mov_b64 exec, s[6:7]
	s_cbranch_execz .LBB0_1040
	buffer_wbl2 sc1
	s_waitcnt vmcnt(0)
	s_load_dwordx2 s[6:7], s[58:59], 0x58
	s_mov_b64 s[8:9], exec
	v_mbcnt_lo_u32_b32 v1, s8, 0
	v_mbcnt_hi_u32_b32 v1, s9, v1
	v_cmp_eq_u32_e32 vcc, 0, v1
	s_waitcnt lgkmcnt(0)
	global_load_dword v0, v205, s[6:7] offset:40
	s_and_saveexec_b64 s[12:13], vcc
	s_cbranch_execz .LBB0_1033
	s_bcnt1_i32_b64 s1, s[8:9]
	v_mov_b32_e32 v2, s1
	global_atomic_add v2, v205, v2, s[6:7] offset:32 sc0

; __global__ void __launch_bounds__(512) fwd_megakernel(Params p) {
;   __shared__ __attribute__((aligned(1024))) char shm[131072];
;   cg::grid_group grid = cg::this_grid();
;   const int wid_s_ = __builtin_amdgcn_readfirstlane((int)(threadIdx.x >> 6));
	.amdhsa_kernel _Z14fwd_megakernel6Params
		.amdhsa_group_segment_fixed_size 131072
		.amdhsa_private_segment_fixed_size 0
		.amdhsa_kernarg_size 392
		.amdhsa_user_sgpr_count 2
		.amdhsa_user_sgpr_dispatch_ptr 0
		.amdhsa_user_sgpr_queue_ptr 0
		.amdhsa_user_sgpr_kernarg_segment_ptr 1
		.amdhsa_user_sgpr_dispatch_id 0
		.amdhsa_user_sgpr_kernarg_preload_length 0
		.amdhsa_user_sgpr_kernarg_preload_offset 0
		.amdhsa_user_sgpr_private_segment_size 0
		.amdhsa_uses_dynamic_stack 0
		.amdhsa_enable_private_segment 0
		.amdhsa_system_sgpr_workgroup_id_x 1
		.amdhsa_system_sgpr_workgroup_id_y 0
		.amdhsa_system_sgpr_workgroup_id_z 0
		.amdhsa_system_sgpr_workgroup_info 0
		.amdhsa_system_vgpr_workitem_id 2
		.amdhsa_next_free_vgpr 256
		.amdhsa_next_free_sgpr 102
		.amdhsa_accum_offset 256
		.amdhsa_reserve_vcc 1
		.amdhsa_float_round_mode_32 0
		.amdhsa_float_round_mode_16_64 0
		.amdhsa_float_denorm_mode_32 3
		.amdhsa_float_denorm_mode_16_64 3
		.amdhsa_dx10_clamp 1
		.amdhsa_ieee_mode 1
		.amdhsa_fp16_overflow 0
		.amdhsa_tg_split 0
		.amdhsa_exception_fp_ieee_invalid_op 0
		.amdhsa_exception_fp_denorm_src 0
		.amdhsa_exception_fp_ieee_div_zero 0
		.amdhsa_exception_fp_ieee_overflow 0
		.amdhsa_exception_fp_ieee_underflow 0
		.amdhsa_exception_fp_ieee_inexact 0
		.amdhsa_exception_int_div_zero 0
	.end_amdhsa_kernel

amdhsa.kernels:
  - .agpr_count:     0
    .args:
      - .offset:         0
        .size:           136
        .value_kind:     by_value
      - .offset:         136
        .size:           4
        .value_kind:     hidden_block_count_x
      - .offset:         140
        .size:           4
        .value_kind:     hidden_block_count_y
      - .offset:         144
        .size:           4
        .value_kind:     hidden_block_count_z
      - .offset:         148
        .size:           2
        .value_kind:     hidden_group_size_x
      - .offset:         150
        .size:           2
        .value_kind:     hidden_group_size_y
      - .offset:         152
        .size:           2
        .value_kind:     hidden_group_size_z
      - .offset:         154
        .size:           2
        .value_kind:     hidden_remainder_x
      - .offset:         156
        .size:           2
        .value_kind:     hidden_remainder_y
      - .offset:         158
        .size:           2
        .value_kind:     hidden_remainder_z
      - .offset:         176
        .size:           8
        .value_kind:     hidden_global_offset_x
      - .offset:         184
        .size:           8
        .value_kind:     hidden_global_offset_y
      - .offset:         192
        .size:           8
        .value_kind:     hidden_global_offset_z
      - .offset:         200
        .size:           2
        .value_kind:     hidden_grid_dims
      - .offset:         224
        .size:           8
        .value_kind:     hidden_multigrid_sync_arg
    .group_segment_fixed_size: 131072
    .kernarg_segment_align: 8
    .kernarg_segment_size: 392
    .language:       OpenCL C
    .language_version:
      - 2
      - 0
    .max_flat_workgroup_size: 512
    .name:           _Z14fwd_megakernel6Params
    .private_segment_fixed_size: 0
    .sgpr_count:     108
    .sgpr_spill_count: 76
    .symbol:         _Z14fwd_megakernel6Params.kd
    .uniform_work_group_size: 1
    .uses_dynamic_stack: false
    .vgpr_count:     256
    .vgpr_spill_count: 0
    .wavefront_size: 64
